# speedup vs baseline: 1.0066x; 1.0059x over previous
; __global__ void __launch_bounds__(NTHREADS, 2) fwd_megakernel(Params p_arg) {
;     ...
;   const int lok_k = (int)xb.local_ok;
;   const int vxcd_k = __builtin_amdgcn_readfirstlane((int)(blockIdx.x & 7) + lok_k * ((int)xb.x - (int)(blockIdx.x & 7)));
;   const int vslot_k = __builtin_amdgcn_readfirstlane((int)(blockIdx.x >> 3) + lok_k * ((int)xb.rank - (int)(blockIdx.x >> 3)));
;     ...
;     for (int rep_ = 0; rep_ < REP_PREP; ++rep_) {
;     ...
;     { PHASE_BEGIN(0);
;   {
;     for (int t = blockIdx.x; t < NLAYER * 3584; t += gridDim.x) {
;       int l = t / 3584, r = t - l * 3584;
;       u16* wl = WB + (size_t)l * WLAYER_E;
;       if (r < 960) { transpose_tile(pk->w_in + (size_t)l * 1024 * INW, wl + WOFF_IN, 1024, INW, r / 60, r % 60, 1, shm, tid); }
.LBB0_34:
	s_or_b64 exec, exec, s[34:35]
	v_mov_b32_e32 v3, 0
	s_waitcnt lgkmcnt(0)
	s_barrier
	ds_read_b128 v[4:7], v3
	s_and_b32 s6, s2, 7
	s_waitcnt lgkmcnt(0)
	s_barrier
	v_readfirstlane_b32 s4, v5
	v_readfirstlane_b32 s7, v4
	v_readfirstlane_b32 s16, v7
	v_writelane_b32 v255, s4, 1
	v_readfirstlane_b32 s4, v6
	s_lshr_b32 s10, s16, 16
	s_and_b32 s5, s16, 0xffff
	v_writelane_b32 v255, s4, 2
	v_writelane_b32 v255, s0, 3
	s_mov_b64 s[8:9], s[0:1]
	s_sub_i32 s4, s7, s6
	v_writelane_b32 v255, s1, 4
	v_mbcnt_lo_u32_b32 v0, -1, 0
	v_mbcnt_hi_u32_b32 v0, -1, v0
	s_mul_i32 s4, s10, s4
	v_readlane_b32 s0, v255, 0
	s_add_i32 s6, s4, s6
	s_lshr_b32 s4, s2, 3
	v_add_u32_e32 v0, s0, v0
	s_load_dwordx2 s[0:1], s[8:9], 0x98
	s_load_dwordx2 s[42:43], s[8:9], 0x88
	s_load_dwordx2 s[44:45], s[8:9], 0x80
	s_load_dwordx2 s[46:47], s[8:9], 0x70
	s_load_dwordx2 s[48:49], s[8:9], 0x68
	s_load_dwordx2 s[50:51], s[8:9], 0x60
	s_load_dwordx2 s[52:53], s[8:9], 0x28
	s_sub_i32 s5, s5, s4
	s_mul_i32 s40, s5, s10
	s_add_i32 s40, s40, s4
	v_writelane_b32 v255, s10, 5
	s_cmpk_lt_i32 s2, 0x3800
	v_readfirstlane_b32 s17, v0
	s_cbranch_scc0 .LBB0_59
	v_ashrrev_i32_e32 v1, 3, v0
	v_lshlrev_b32_e32 v2, 3, v0
	v_and_b32_e32 v4, 56, v2
	v_lshlrev_b32_e32 v2, 1, v1
	s_movk_i32 s4, 0x84
	v_mad_u32_u24 v8, v4, s4, v2
	v_mul_lo_u32 v2, v1, s4
	v_lshl_add_u32 v9, v4, 1, v2
	v_and_b32_e32 v10, 31, v1
	s_lshl_b32 s18, s2, 2
	s_lshl_b32 s19, s3, 2
	s_lshl_b32 s20, s2, 6
	s_lshl_b32 s21, s3, 6
	s_mov_b32 s5, 0
	s_movk_i32 s26, 0x1600
	s_movk_i32 s27, 0x5800
	s_movk_i32 s28, 0xaff
	s_movk_i32 s29, 0x3c00
	s_movk_i32 s30, 0x6ff
	v_lshlrev_b32_e32 v2, 2, v4
	v_lshlrev_b32_e32 v4, 1, v4
	v_mov_b32_e32 v11, 0xfffff900
	v_mov_b32_e32 v12, 0xfffff500
	s_mov_b32 s31, s2
	s_branch .LBB0_38

; __device__ __forceinline__ u16 f2bf(float a) { return (u16)(pack2(a, 0.f) & 0xffffu); }
;     ...
;   {
;     int k = t >> 3, n0 = (t & 7) * 8;
;     const float4* s = (const float4*)(src + (size_t)(kt * 64 + k) * N + ntile * 64 + n0);
;     float4 a = s[0], b = s[1];
;     tl[(n0 + 0) * 66 + k] = f2bf(a.x); tl[(n0 + 1) * 66 + k] = f2bf(a.y);
;     tl[(n0 + 2) * 66 + k] = f2bf(a.z); tl[(n0 + 3) * 66 + k] = f2bf(a.w);
;     tl[(n0 + 4) * 66 + k] = f2bf(b.x); tl[(n0 + 5) * 66 + k] = f2bf(b.y);
;     tl[(n0 + 6) * 66 + k] = f2bf(b.z); tl[(n0 + 7) * 66 + k] = f2bf(b.w);
;   }
;   __syncthreads();
;   {
;     int n = t >> 3, kk0 = (t & 7) * 8;
;     int ng = ntile * 64 + n, np = ng;
;     if (mode == 1) {
;       if (ng >= 1792) { int j = ng - 1792; int hb = 0; if (j >= 1024) { j -= 1024; hb = 32; } np = 1792 + (j >> 5) * 64 + hb + (j & 31); }
;     } else if (mode == 2) {
;       int j = ng, hb = 0; if (j >= DFF) { j -= DFF; hb = 32; } np = (j >> 5) * 64 + hb + (j & 31);
;     }
;     const uint32_t* r = (const uint32_t*)(tl + n * 66 + kk0);
;     uint4 v = make_uint4(r[0], r[1], r[2], r[3]);
;     *(uint4*)(dst + (size_t)np * dld + kt * 64 + kk0) = v;
; __global__ void __launch_bounds__(NTHREADS, 2) fwd_megakernel(Params p_arg) {
;     ...
;     for (int t = blockIdx.x; t < NLAYER * 3584; t += gridDim.x) {
;       int l = t / 3584, r = t - l * 3584;
;       u16* wl = WB + (size_t)l * WLAYER_E;
;       if (r < 960) { transpose_tile(pk->w_in + (size_t)l * 1024 * INW, wl + WOFF_IN, 1024, INW, r / 60, r % 60, 1, shm, tid); }
;       else if (r < 1088) { r -= 960; transpose_tile(pk->w_a + (size_t)l * 512 * 1024, wl + WOFF_A, 512, 1024, r / 16, r % 16, 0, shm, tid, 1024); }
;       else if (r < 1216) { r -= 1088; transpose_tile(pk->w_b + (size_t)l * 512 * 1024, wl + WOFF_A + 512, 512, 1024, r / 16, r % 16, 0, shm, tid, 1024); }
;       else if (r < 1472) { r -= 1216; transpose_tile(pk->w_o + (size_t)l * 1024 * 1024, wl + WOFF_O, 1024, 1024, r / 16, r % 16, 0, shm, tid); }
;       else if (r < 2880) { r -= 1472; transpose_tile(pk->w_ffn_in + (size_t)l * 1024 * 2 * DFF, wl + WOFF_FI, 1024, 2 * DFF, r / 88, r % 88, 2, shm, tid); }
;       else { r -= 2880; transpose_tile(pk->w_ffn_out + (size_t)l * DFF * 1024, wl + WOFF_FO, DFF, 1024, r / 16, r % 16, 0, shm, tid); }
.LBB0_38:
	s_mul_hi_i32 s4, s31, 0x92492493
	s_add_i32 s4, s4, s31
	s_lshr_b32 s10, s4, 31
	s_ashr_i32 s4, s4, 11
	s_add_i32 s12, s4, s10
	s_mul_i32 s4, s12, 0xfffff200
	s_add_i32 s33, s31, s4
	s_ashr_i32 s13, s12, 31
	s_mul_i32 s10, s12, 0x1c40000
	s_mul_hi_i32 s4, s12, 0x1c40000
	s_waitcnt lgkmcnt(0)
	s_add_u32 s10, s0, s10
	s_addc_u32 s11, s1, s4
	s_cmpk_gt_i32 s33, 0x3bf
	s_mov_b64 s[14:15], -1
	s_cbranch_scc0 .LBB0_56
	s_cmpk_gt_u32 s33, 0x43f
	s_cbranch_scc0 .LBB0_53
	s_cmpk_gt_u32 s33, 0x4bf
	s_cbranch_scc0 .LBB0_50
	s_cmpk_gt_u32 s33, 0x5bf
	s_cbranch_scc0 .LBB0_47
	s_cmpk_gt_u32 s33, 0xb3f
	s_cbranch_scc0 .LBB0_44
	s_mov_b64 s[14:15], s[42:43]
	s_mul_i32 s34, s12, 0xb00000
	s_mul_hi_i32 s4, s12, 0xb00000
	s_mul_i32 s35, s12, 0xffffc800
	v_mov_b32_e32 v5, v3
	s_waitcnt lgkmcnt(0)
	s_add_u32 s14, s14, s34
	s_addc_u32 s15, s15, s4
	s_add_i32 s4, s18, s35
	s_andn2_b32 s4, s4, 63
	s_add_i32 s34, s4, 0xffffd300
	v_add_u32_e32 v6, s34, v1
	v_ashrrev_i32_e32 v7, 31, v6
	v_lshlrev_b64 v[6:7], 12, v[6:7]
	v_lshl_add_u64 v[6:7], s[14:15], 0, v[6:7]
	s_and_b32 s14, s20, 0x3c0
	s_lshl_b32 s4, s14, 2
	v_lshl_add_u64 v[6:7], v[6:7], 0, s[4:5]
	v_lshl_add_u64 v[6:7], v[6:7], 0, v[2:3]
	global_load_dwordx4 v[14:17], v[6:7], off
	global_load_dwordx4 v[18:21], v[6:7], off offset:16
	v_mov_b64_e32 v[6:7], s[10:11]
	v_add_u32_e32 v13, s14, v1
	s_mov_b32 s35, s5
	v_mad_i64_i32 v[6:7], s[14:15], v13, s26, v[6:7]
	v_lshl_add_u64 v[6:7], s[34:35], 1, v[6:7]
	v_lshl_add_u64 v[6:7], v[6:7], 0, v[4:5]
	v_add_co_u32_e32 v6, vcc, 0x1680000, v6
	s_mov_b64 s[14:15], 0
	s_nop 0
	v_addc_co_u32_e32 v7, vcc, 0, v7, vcc
	s_waitcnt vmcnt(1)
	v_cvt_pk_bf16_f32 v5, v14, s0
	v_cvt_pk_bf16_f32 v13, v15, s0
	v_cvt_pk_bf16_f32 v14, v16, s0
	v_cvt_pk_bf16_f32 v15, v17, s0
	s_waitcnt vmcnt(0)
	v_cvt_pk_bf16_f32 v16, v18, s0
	v_cvt_pk_bf16_f32 v17, v19, s0
	v_cvt_pk_bf16_f32 v18, v20, s0
	v_cvt_pk_bf16_f32 v19, v21, s0
	ds_write_b16 v8, v5
	ds_write_b16 v8, v13 offset:132
	ds_write_b16 v8, v14 offset:264
	ds_write_b16 v8, v15 offset:396
	ds_write_b16 v8, v16 offset:528
	ds_write_b16 v8, v17 offset:660
	ds_write_b16 v8, v18 offset:792
	ds_write_b16 v8, v19 offset:924
	s_waitcnt lgkmcnt(0)
	s_barrier
	ds_read2_b32 v[14:15], v9 offset1:1
	ds_read2_b32 v[16:17], v9 offset0:2 offset1:3
	s_waitcnt lgkmcnt(0)
	global_store_dwordx4 v[6:7], v[14:17], off
.LBB0_44:
	s_andn2_b64 vcc, exec, s[14:15]
	s_cbranch_vccnz .LBB0_46
	s_mov_b64 s[14:15], s[44:45]
	s_mul_i32 s34, s12, 0x1600000
	s_mul_hi_i32 s4, s12, 0x1600000
	s_waitcnt lgkmcnt(0)
	s_add_u32 s14, s14, s34
	s_addc_u32 s15, s15, s4
	s_add_i32 s4, s33, 0xfa40
	s_and_b32 s34, s4, 0xffff
	s_mul_i32 s34, s34, 0xba2f
	s_lshr_b32 s35, s34, 16
	s_lshr_b32 s34, s34, 22
	s_mulk_i32 s34, 0x58
	s_sub_i32 s4, s4, s34
	s_and_b32 s34, s35, 0xffc0
	v_add_u32_e32 v5, s34, v1
	v_mov_b64_e32 v[6:7], s[14:15]
	v_mad_i64_i32 v[6:7], s[14:15], v5, s27, v[6:7]
	s_lshl_b32 s4, s4, 6
	s_and_b32 s14, s4, 0xffc0
	s_lshl_b32 s4, s14, 2
	v_lshl_add_u64 v[6:7], v[6:7], 0, s[4:5]
	v_lshl_add_u64 v[6:7], v[6:7], 0, v[2:3]
	global_load_dwordx4 v[14:17], v[6:7], off
	global_load_dwordx4 v[18:21], v[6:7], off offset:16
	v_add_u32_e32 v6, s14, v1
	v_add_u32_e32 v7, 0xfffff500, v6
	v_cmp_lt_i32_e32 vcc, s28, v6
	s_lshl_b32 s4, s34, 1
	v_mov_b32_e32 v5, v3
	v_cndmask_b32_e32 v6, v6, v7, vcc
	v_lshlrev_b32_e32 v7, 1, v6
	v_cndmask_b32_e64 v13, 0, 32, vcc
	v_and_b32_e32 v6, 31, v6
	v_and_b32_e32 v7, 0xffffffc0, v7
	v_or3_b32 v6, v6, v13, v7
	v_ashrrev_i32_e32 v7, 31, v6
	v_lshlrev_b64 v[6:7], 11, v[6:7]
	v_lshl_add_u64 v[6:7], s[10:11], 0, v[6:7]
	v_lshl_add_u64 v[6:7], v[6:7], 0, s[4:5]
	v_lshl_add_u64 v[6:7], v[6:7], 0, v[4:5]
	v_add_co_u32_e32 v6, vcc, 0xb80000, v6
	s_waitcnt vmcnt(1)
	v_cvt_pk_bf16_f32 v5, v14, s0
	v_cvt_pk_bf16_f32 v13, v15, s0
	v_cvt_pk_bf16_f32 v14, v16, s0
	v_cvt_pk_bf16_f32 v15, v17, s0
	s_waitcnt vmcnt(0)
	v_cvt_pk_bf16_f32 v16, v18, s0
	v_cvt_pk_bf16_f32 v17, v19, s0
	v_cvt_pk_bf16_f32 v18, v20, s0
	v_cvt_pk_bf16_f32 v19, v21, s0
	ds_write_b16 v8, v5
	ds_write_b16 v8, v13 offset:132
	ds_write_b16 v8, v14 offset:264
	ds_write_b16 v8, v15 offset:396
	ds_write_b16 v8, v16 offset:528
	ds_write_b16 v8, v17 offset:660
	ds_write_b16 v8, v18 offset:792
	ds_write_b16 v8, v19 offset:924
	s_waitcnt lgkmcnt(0)
	s_barrier
	ds_read2_b32 v[14:15], v9 offset1:1
	ds_read2_b32 v[16:17], v9 offset0:2 offset1:3
	v_addc_co_u32_e32 v7, vcc, 0, v7, vcc
	s_waitcnt lgkmcnt(0)
	global_store_dwordx4 v[6:7], v[14:17], off

; __device__ __forceinline__ u16 f2bf(float a) { return (u16)(pack2(a, 0.f) & 0xffffu); }
;     ...
;   {
;     int k = t >> 3, n0 = (t & 7) * 8;
;     const float4* s = (const float4*)(src + (size_t)(kt * 64 + k) * N + ntile * 64 + n0);
;     float4 a = s[0], b = s[1];
;     tl[(n0 + 0) * 66 + k] = f2bf(a.x); tl[(n0 + 1) * 66 + k] = f2bf(a.y);
;     tl[(n0 + 2) * 66 + k] = f2bf(a.z); tl[(n0 + 3) * 66 + k] = f2bf(a.w);
;     tl[(n0 + 4) * 66 + k] = f2bf(b.x); tl[(n0 + 5) * 66 + k] = f2bf(b.y);
;     tl[(n0 + 6) * 66 + k] = f2bf(b.z); tl[(n0 + 7) * 66 + k] = f2bf(b.w);
;   }
;   __syncthreads();
;   {
;     int n = t >> 3, kk0 = (t & 7) * 8;
;     int ng = ntile * 64 + n, np = ng;
;     if (mode == 1) {
;       if (ng >= 1792) { int j = ng - 1792; int hb = 0; if (j >= 1024) { j -= 1024; hb = 32; } np = 1792 + (j >> 5) * 64 + hb + (j & 31); }
;     } else if (mode == 2) {
;       int j = ng, hb = 0; if (j >= DFF) { j -= DFF; hb = 32; } np = (j >> 5) * 64 + hb + (j & 31);
;     }
;     const uint32_t* r = (const uint32_t*)(tl + n * 66 + kk0);
;     uint4 v = make_uint4(r[0], r[1], r[2], r[3]);
;     *(uint4*)(dst + (size_t)np * dld + kt * 64 + kk0) = v;
; __global__ void __launch_bounds__(NTHREADS, 2) fwd_megakernel(Params p_arg) {
;     ...
;       else if (r < 1472) { r -= 1216; transpose_tile(pk->w_o + (size_t)l * 1024 * 1024, wl + WOFF_O, 1024, 1024, r / 16, r % 16, 0, shm, tid); }
.LBB0_47:
	s_andn2_b64 vcc, exec, s[14:15]
	s_cbranch_vccnz .LBB0_49
	s_mov_b64 s[14:15], s[46:47]
	s_lshl_b64 s[34:35], s[12:13], 22
	s_mul_i32 s4, s12, 0xffffc800
	v_mov_b32_e32 v5, v3
	s_waitcnt lgkmcnt(0)
	s_add_u32 s14, s14, s34
	s_addc_u32 s15, s15, s35
	s_add_i32 s4, s18, s4
	s_and_b32 s4, s4, 0x1fc0
	s_add_i32 s34, s4, 0xffffed00
	v_add_u32_e32 v6, s34, v1
	v_ashrrev_i32_e32 v7, 31, v6
	s_and_b32 s36, s20, 0x3c0
	v_lshlrev_b64 v[6:7], 12, v[6:7]
	v_lshl_add_u64 v[6:7], s[14:15], 0, v[6:7]
	s_lshl_b32 s4, s36, 2
	v_lshl_add_u64 v[6:7], v[6:7], 0, s[4:5]
	v_lshl_add_u64 v[6:7], v[6:7], 0, v[2:3]
	global_load_dwordx4 v[14:17], v[6:7], off
	global_load_dwordx4 v[18:21], v[6:7], off offset:16
	v_add_u32_e32 v6, s36, v1
	v_ashrrev_i32_e32 v7, 31, v6
	v_lshlrev_b64 v[6:7], 11, v[6:7]
	s_mov_b32 s35, s5
	v_lshl_add_u64 v[6:7], s[10:11], 0, v[6:7]
	v_lshl_add_u64 v[6:7], s[34:35], 1, v[6:7]
	v_lshl_add_u64 v[6:7], v[6:7], 0, v[4:5]
	v_add_co_u32_e32 v6, vcc, 0x980000, v6
	s_waitcnt vmcnt(1)
	v_cvt_pk_bf16_f32 v5, v14, s0
	v_cvt_pk_bf16_f32 v13, v15, s0
	v_cvt_pk_bf16_f32 v14, v16, s0
	v_cvt_pk_bf16_f32 v15, v17, s0
	s_waitcnt vmcnt(0)
	v_cvt_pk_bf16_f32 v16, v18, s0
	v_cvt_pk_bf16_f32 v17, v19, s0
	v_cvt_pk_bf16_f32 v18, v20, s0
	v_cvt_pk_bf16_f32 v19, v21, s0
	ds_write_b16 v8, v5
	ds_write_b16 v8, v13 offset:132
	ds_write_b16 v8, v14 offset:264
	ds_write_b16 v8, v15 offset:396
	ds_write_b16 v8, v16 offset:528
	ds_write_b16 v8, v17 offset:660
	ds_write_b16 v8, v18 offset:792
	ds_write_b16 v8, v19 offset:924
	s_waitcnt lgkmcnt(0)
	s_barrier
	ds_read2_b32 v[14:15], v9 offset1:1
	ds_read2_b32 v[16:17], v9 offset0:2 offset1:3
	v_addc_co_u32_e32 v7, vcc, 0, v7, vcc
	s_waitcnt lgkmcnt(0)
	global_store_dwordx4 v[6:7], v[14:17], off

; __device__ __forceinline__ u16 f2bf(float a) { return (u16)(pack2(a, 0.f) & 0xffffu); }
;     ...
;   {
;     int k = t >> 3, n0 = (t & 7) * 8;
;     const float4* s = (const float4*)(src + (size_t)(kt * 64 + k) * N + ntile * 64 + n0);
;     float4 a = s[0], b = s[1];
;     tl[(n0 + 0) * 66 + k] = f2bf(a.x); tl[(n0 + 1) * 66 + k] = f2bf(a.y);
;     tl[(n0 + 2) * 66 + k] = f2bf(a.z); tl[(n0 + 3) * 66 + k] = f2bf(a.w);
;     tl[(n0 + 4) * 66 + k] = f2bf(b.x); tl[(n0 + 5) * 66 + k] = f2bf(b.y);
;     tl[(n0 + 6) * 66 + k] = f2bf(b.z); tl[(n0 + 7) * 66 + k] = f2bf(b.w);
;   }
;   __syncthreads();
;   {
;     int n = t >> 3, kk0 = (t & 7) * 8;
;     int ng = ntile * 64 + n, np = ng;
;     if (mode == 1) {
;       if (ng >= 1792) { int j = ng - 1792; int hb = 0; if (j >= 1024) { j -= 1024; hb = 32; } np = 1792 + (j >> 5) * 64 + hb + (j & 31); }
;     } else if (mode == 2) {
;       int j = ng, hb = 0; if (j >= DFF) { j -= DFF; hb = 32; } np = (j >> 5) * 64 + hb + (j & 31);
;     }
;     const uint32_t* r = (const uint32_t*)(tl + n * 66 + kk0);
;     uint4 v = make_uint4(r[0], r[1], r[2], r[3]);
;     *(uint4*)(dst + (size_t)np * dld + kt * 64 + kk0) = v;
; __global__ void __launch_bounds__(NTHREADS, 2) fwd_megakernel(Params p_arg) {
;     ...
;       else if (r < 1216) { r -= 1088; transpose_tile(pk->w_b + (size_t)l * 512 * 1024, wl + WOFF_A + 512, 512, 1024, r / 16, r % 16, 0, shm, tid, 1024); }
.LBB0_50:
	s_andn2_b64 vcc, exec, s[14:15]
	s_cbranch_vccnz .LBB0_52
	s_mov_b64 s[14:15], s[48:49]
	s_lshl_b64 s[34:35], s[12:13], 21
	s_mul_i32 s4, s12, 0xffffc800
	v_mov_b32_e32 v5, v3
	s_waitcnt lgkmcnt(0)
	s_add_u32 s14, s14, s34
	s_addc_u32 s15, s15, s35
	s_add_i32 s4, s18, s4
	s_and_b32 s4, s4, 0x1fc0
	s_add_i32 s34, s4, 0xffffef00
	v_add_u32_e32 v6, s34, v1
	v_ashrrev_i32_e32 v7, 31, v6
	s_and_b32 s36, s20, 0x3c0
	v_lshlrev_b64 v[6:7], 12, v[6:7]
	v_lshl_add_u64 v[6:7], s[14:15], 0, v[6:7]
	s_lshl_b32 s4, s36, 2
	v_lshl_add_u64 v[6:7], v[6:7], 0, s[4:5]
	v_lshl_add_u64 v[6:7], v[6:7], 0, v[2:3]
	global_load_dwordx4 v[14:17], v[6:7], off
	global_load_dwordx4 v[18:21], v[6:7], off offset:16
	v_add_u32_e32 v6, s36, v1
	v_ashrrev_i32_e32 v7, 31, v6
	v_lshlrev_b64 v[6:7], 11, v[6:7]
	s_mov_b32 s35, s5
	v_lshl_add_u64 v[6:7], s[10:11], 0, v[6:7]
	v_lshl_add_u64 v[6:7], s[34:35], 1, v[6:7]
	v_lshl_add_u64 v[6:7], v[6:7], 0, v[4:5]
	v_add_co_u32_e32 v6, vcc, 0x780000, v6
	s_waitcnt vmcnt(1)
	v_cvt_pk_bf16_f32 v5, v14, s0
	v_cvt_pk_bf16_f32 v13, v15, s0
	v_cvt_pk_bf16_f32 v14, v16, s0
	v_cvt_pk_bf16_f32 v15, v17, s0
	s_waitcnt vmcnt(0)
	v_cvt_pk_bf16_f32 v16, v18, s0
	v_cvt_pk_bf16_f32 v17, v19, s0
	v_cvt_pk_bf16_f32 v18, v20, s0
	v_cvt_pk_bf16_f32 v19, v21, s0
	ds_write_b16 v8, v5
	ds_write_b16 v8, v13 offset:132
	ds_write_b16 v8, v14 offset:264
	ds_write_b16 v8, v15 offset:396
	ds_write_b16 v8, v16 offset:528
	ds_write_b16 v8, v17 offset:660
	ds_write_b16 v8, v18 offset:792
	ds_write_b16 v8, v19 offset:924
	s_waitcnt lgkmcnt(0)
	s_barrier
	ds_read2_b32 v[14:15], v9 offset1:1
	ds_read2_b32 v[16:17], v9 offset0:2 offset1:3
	v_addc_co_u32_e32 v7, vcc, 0, v7, vcc
	s_waitcnt lgkmcnt(0)
	global_store_dwordx4 v[6:7], v[14:17], off offset:1024

; __device__ __forceinline__ u16 f2bf(float a) { return (u16)(pack2(a, 0.f) & 0xffffu); }
;     ...
;   {
;     int k = t >> 3, n0 = (t & 7) * 8;
;     const float4* s = (const float4*)(src + (size_t)(kt * 64 + k) * N + ntile * 64 + n0);
;     float4 a = s[0], b = s[1];
;     tl[(n0 + 0) * 66 + k] = f2bf(a.x); tl[(n0 + 1) * 66 + k] = f2bf(a.y);
;     tl[(n0 + 2) * 66 + k] = f2bf(a.z); tl[(n0 + 3) * 66 + k] = f2bf(a.w);
;     tl[(n0 + 4) * 66 + k] = f2bf(b.x); tl[(n0 + 5) * 66 + k] = f2bf(b.y);
;     tl[(n0 + 6) * 66 + k] = f2bf(b.z); tl[(n0 + 7) * 66 + k] = f2bf(b.w);
;   }
;   __syncthreads();
;   {
;     int n = t >> 3, kk0 = (t & 7) * 8;
;     int ng = ntile * 64 + n, np = ng;
;     if (mode == 1) {
;       if (ng >= 1792) { int j = ng - 1792; int hb = 0; if (j >= 1024) { j -= 1024; hb = 32; } np = 1792 + (j >> 5) * 64 + hb + (j & 31); }
;     } else if (mode == 2) {
;       int j = ng, hb = 0; if (j >= DFF) { j -= DFF; hb = 32; } np = (j >> 5) * 64 + hb + (j & 31);
;     }
;     const uint32_t* r = (const uint32_t*)(tl + n * 66 + kk0);
;     uint4 v = make_uint4(r[0], r[1], r[2], r[3]);
;     *(uint4*)(dst + (size_t)np * dld + kt * 64 + kk0) = v;
; __global__ void __launch_bounds__(NTHREADS, 2) fwd_megakernel(Params p_arg) {
;     ...
;       else if (r < 1088) { r -= 960; transpose_tile(pk->w_a + (size_t)l * 512 * 1024, wl + WOFF_A, 512, 1024, r / 16, r % 16, 0, shm, tid, 1024); }
.LBB0_53:
	s_andn2_b64 vcc, exec, s[14:15]
	s_cbranch_vccnz .LBB0_55
	s_mov_b64 s[14:15], s[50:51]
	s_lshl_b64 s[34:35], s[12:13], 21
	s_mul_i32 s4, s12, 0xffffc800
	v_mov_b32_e32 v5, v3
	s_waitcnt lgkmcnt(0)
	s_add_u32 s14, s14, s34
	s_addc_u32 s15, s15, s35
	s_add_i32 s4, s18, s4
	s_and_b32 s4, s4, 0x1fc0
	s_add_i32 s34, s4, 0xfffff100
	v_add_u32_e32 v6, s34, v1
	v_ashrrev_i32_e32 v7, 31, v6
	s_and_b32 s13, s20, 0x3c0
	v_lshlrev_b64 v[6:7], 12, v[6:7]
	v_lshl_add_u64 v[6:7], s[14:15], 0, v[6:7]
	s_lshl_b32 s4, s13, 2
	v_lshl_add_u64 v[6:7], v[6:7], 0, s[4:5]
	v_lshl_add_u64 v[6:7], v[6:7], 0, v[2:3]
	global_load_dwordx4 v[14:17], v[6:7], off
	global_load_dwordx4 v[18:21], v[6:7], off offset:16
	v_add_u32_e32 v6, s13, v1
	v_ashrrev_i32_e32 v7, 31, v6
	v_lshlrev_b64 v[6:7], 11, v[6:7]
	s_mov_b32 s35, s5
	v_lshl_add_u64 v[6:7], s[10:11], 0, v[6:7]
	v_lshl_add_u64 v[6:7], s[34:35], 1, v[6:7]
	v_lshl_add_u64 v[6:7], v[6:7], 0, v[4:5]
	v_add_co_u32_e32 v6, vcc, 0x780000, v6
	s_waitcnt vmcnt(1)
	v_cvt_pk_bf16_f32 v5, v14, s0
	v_cvt_pk_bf16_f32 v13, v15, s0
	v_cvt_pk_bf16_f32 v14, v16, s0
	v_cvt_pk_bf16_f32 v15, v17, s0
	s_waitcnt vmcnt(0)
	v_cvt_pk_bf16_f32 v16, v18, s0
	v_cvt_pk_bf16_f32 v17, v19, s0
	v_cvt_pk_bf16_f32 v18, v20, s0
	v_cvt_pk_bf16_f32 v19, v21, s0
	ds_write_b16 v8, v5
	ds_write_b16 v8, v13 offset:132
	ds_write_b16 v8, v14 offset:264
	ds_write_b16 v8, v15 offset:396
	ds_write_b16 v8, v16 offset:528
	ds_write_b16 v8, v17 offset:660
	ds_write_b16 v8, v18 offset:792
	ds_write_b16 v8, v19 offset:924
	s_waitcnt lgkmcnt(0)
	s_barrier
	ds_read2_b32 v[14:15], v9 offset1:1
	ds_read2_b32 v[16:17], v9 offset0:2 offset1:3
	v_addc_co_u32_e32 v7, vcc, 0, v7, vcc
	s_waitcnt lgkmcnt(0)
	global_store_dwordx4 v[6:7], v[14:17], off

; __device__ __forceinline__ u16 f2bf(float a) { return (u16)(pack2(a, 0.f) & 0xffffu); }
;     ...
;   {
;     int k = t >> 3, n0 = (t & 7) * 8;
;     const float4* s = (const float4*)(src + (size_t)(kt * 64 + k) * N + ntile * 64 + n0);
;     float4 a = s[0], b = s[1];
;     tl[(n0 + 0) * 66 + k] = f2bf(a.x); tl[(n0 + 1) * 66 + k] = f2bf(a.y);
;     tl[(n0 + 2) * 66 + k] = f2bf(a.z); tl[(n0 + 3) * 66 + k] = f2bf(a.w);
;     tl[(n0 + 4) * 66 + k] = f2bf(b.x); tl[(n0 + 5) * 66 + k] = f2bf(b.y);
;     tl[(n0 + 6) * 66 + k] = f2bf(b.z); tl[(n0 + 7) * 66 + k] = f2bf(b.w);
;   }
;   __syncthreads();
;   {
;     int n = t >> 3, kk0 = (t & 7) * 8;
;     int ng = ntile * 64 + n, np = ng;
;     if (mode == 1) {
;       if (ng >= 1792) { int j = ng - 1792; int hb = 0; if (j >= 1024) { j -= 1024; hb = 32; } np = 1792 + (j >> 5) * 64 + hb + (j & 31); }
;     } else if (mode == 2) {
;       int j = ng, hb = 0; if (j >= DFF) { j -= DFF; hb = 32; } np = (j >> 5) * 64 + hb + (j & 31);
;     }
;     const uint32_t* r = (const uint32_t*)(tl + n * 66 + kk0);
;     uint4 v = make_uint4(r[0], r[1], r[2], r[3]);
;     *(uint4*)(dst + (size_t)np * dld + kt * 64 + kk0) = v;
; __global__ void __launch_bounds__(NTHREADS, 2) fwd_megakernel(Params p_arg) {
;     ...
;       if (r < 960) { transpose_tile(pk->w_in + (size_t)l * 1024 * INW, wl + WOFF_IN, 1024, INW, r / 60, r % 60, 1, shm, tid); }
.LBB0_56:
	s_andn2_b64 vcc, exec, s[14:15]
	s_cbranch_vccnz .LBB0_37
	s_mov_b64 s[14:15], s[52:53]
	s_mul_hi_i32 s4, s12, 0xf00000
	s_mul_i32 s12, s12, 0xf00000
	s_mul_hi_i32 s13, s33, 0x88888889
	s_waitcnt lgkmcnt(0)
	s_add_u32 s14, s14, s12
	s_addc_u32 s15, s15, s4
	s_add_i32 s13, s13, s33
	s_lshr_b32 s4, s13, 31
	s_ashr_i32 s12, s13, 5
	s_add_i32 s4, s12, s4
	s_mul_i32 s12, s4, 60
	s_sub_i32 s13, s33, s12
	s_lshl_b32 s12, s4, 6
	v_add_u32_e32 v5, s12, v1
	v_mov_b64_e32 v[6:7], s[14:15]
	v_mad_i64_i32 v[6:7], s[14:15], v5, s29, v[6:7]
	s_lshl_b32 s14, s13, 6
	s_ashr_i32 s15, s14, 31
	v_lshl_add_u64 v[6:7], s[14:15], 2, v[6:7]
	v_lshl_add_u64 v[6:7], v[6:7], 0, v[2:3]
	global_load_dwordx4 v[14:17], v[6:7], off
	global_load_dwordx4 v[18:21], v[6:7], off offset:16
	v_add_u32_e32 v6, s14, v1
	v_cmp_lt_i32_e32 vcc, s30, v6
	s_waitcnt vmcnt(1)
	v_cvt_pk_bf16_f32 v5, v14, s0
	v_cvt_pk_bf16_f32 v7, v15, s0
	v_cvt_pk_bf16_f32 v13, v16, s0
	v_cvt_pk_bf16_f32 v14, v17, s0
	s_waitcnt vmcnt(0)
	v_cvt_pk_bf16_f32 v15, v18, s0
	v_cvt_pk_bf16_f32 v16, v19, s0
	v_cvt_pk_bf16_f32 v17, v20, s0
	v_cvt_pk_bf16_f32 v18, v21, s0
	ds_write_b16 v8, v5
	ds_write_b16 v8, v7 offset:132
	ds_write_b16 v8, v13 offset:264
	ds_write_b16 v8, v14 offset:396
	ds_write_b16 v8, v15 offset:528
	ds_write_b16 v8, v16 offset:660
	ds_write_b16 v8, v17 offset:792
	ds_write_b16 v8, v18 offset:924
	s_waitcnt lgkmcnt(0)
	s_barrier
	s_and_saveexec_b64 s[14:15], vcc
	s_cbranch_execz .LBB0_36
	v_cmp_lt_u32_e32 vcc, s28, v6
	s_nop 1
	v_cndmask_b32_e32 v7, v11, v12, vcc
	v_add_lshl_u32 v6, v7, v6, 1
	v_cndmask_b32_e64 v5, 0, 32, vcc
	v_and_b32_e32 v6, 0x7fffffc0, v6
	v_or3_b32 v5, v6, v5, v10
	v_add_u32_e32 v6, 0x700, v5
	s_branch .LBB0_36
